# HGRN pass-1 item: first of the three per-item barriers removed (its LDS regions are already ordered by the second and third barriers)
# speedup vs baseline: 1.0057x; 1.0010x over previous
; DEV void hg_load_k(const u16* __restrict__ zb, int tid, u16 (&kr)[16]) {
;   const int wid = tid >> 6, lane = tid & 63, dir = wid >> 2, qu = wid & 3;
;   const u16* kp = zb + (long)(qu * 16) * NINP + C_HF + dir * 512 + lane;
; #pragma unroll
;   for (int i = 0; i < 16; ++i) kr[i] = kp[(long)i * NINP];
; }
; DEV void hg_load_v(const u16* __restrict__ zb, int wid, int lane, u16 (&vr)[8]) {
;   const u16* vp = zb + (long)(wid * 8) * NINP + C_HI + lane;
; #pragma unroll
;   for (int i = 0; i < 8; ++i) vr[i] = vp[(long)i * NINP];
; }
.LBB0_734:
	v_readlane_b32 s6, v253, 2
	s_mov_b32 s11, s10
	s_add_i32 s10, s10, s6
	v_readlane_b32 s7, v253, 3
	s_cmpk_gt_i32 s10, 0x8ff
	s_cselect_b64 s[6:7], -1, 0
	s_cmpk_lt_i32 s10, 0x900
	s_cselect_b32 s8, s10, s11
	s_mov_b32 s50, s8
	s_mov_b32 s19, 0x9000
	s_mov_b32 s18, 0xd000
	s_mov_b32 s17, 0x11000
	s_mov_b32 s16, 0x1e000
	s_ashr_i32 s9, s11, 3
	s_and_b32 s8, s11, 7
	s_mul_hi_i32 s11, s9, 0x38e38e39
	s_lshr_b32 s12, s11, 31
	s_ashr_i32 s11, s11, 3
	s_add_i32 s11, s11, s12
	s_lshl_b32 s12, s11, 3
	s_or_b32 s8, s12, s8
	s_mul_i32 s11, s11, 36
	s_mul_i32 s8, s8, 36
	s_sub_i32 s9, s9, s11
	s_add_i32 s8, s8, s9
	s_mul_hi_i32 s9, s8, 0x38e38e39
	s_lshr_b32 s11, s9, 31
	s_ashr_i32 s9, s9, 3
	s_add_i32 s11, s9, s11
	s_mul_i32 s9, s11, 36
	s_sub_i32 s12, s8, s9
	s_ashr_i32 s8, s11, 3
	s_lshl_b32 s13, s12, 6
	s_mul_hi_i32 s9, s8, 0x900
	s_mulk_i32 s8, 0x900
	s_ashr_i32 s15, s13, 31
	s_add_u32 s8, s8, s13
	s_addc_u32 s9, s9, s15
	s_mulk_i32 s9, 0x4400
	s_mul_hi_u32 s13, s8, 0x4400
	s_add_i32 s13, s13, s9
	s_mulk_i32 s8, 0x4400
	s_add_u32 s8, s88, s8
	s_addc_u32 s9, s89, s13
	s_lshl_b32 s13, s11, 7
	s_and_b32 s13, s13, 0x380
	s_add_u32 s8, s8, s13
	s_addc_u32 s9, s9, 0
	v_lshlrev_b32_e32 v56, 16, v7
	v_and_b32_e32 v57, 0xffff0000, v7
	v_sub_f32_e32 v7, 1.0, v56
	v_log_f32_e32 v7, v7
	v_lshlrev_b32_e32 v46, 16, v6
	v_and_b32_e32 v47, 0xffff0000, v6
	s_mov_b32 s8, s50
	s_and_b32 s9, s8, 7
	s_ashr_i32 s8, s8, 3
	s_mul_hi_i32 s51, s8, 0x38e38e39
	s_lshr_b32 s13, s51, 31
	s_ashr_i32 s51, s51, 3
	s_add_i32 s51, s51, s13
	s_lshl_b32 s13, s51, 3
	s_or_b32 s9, s13, s9
	s_mul_i32 s51, s51, 36
	s_mul_i32 s9, s9, 36
	s_sub_i32 s8, s8, s51
	s_add_i32 s9, s9, s8
	s_mul_hi_i32 s8, s9, 0x38e38e39
	s_lshr_b32 s51, s8, 31
	s_ashr_i32 s8, s8, 3
	s_add_i32 s8, s8, s51
	s_mul_i32 s51, s8, 36
	s_sub_i32 s9, s9, s51
	s_ashr_i32 s51, s8, 3
	s_lshl_b32 s9, s9, 6
	s_mul_hi_i32 s13, s51, 0x900
	s_mulk_i32 s51, 0x900
	s_ashr_i32 s15, s9, 31
	s_add_u32 s9, s51, s9
	s_addc_u32 s51, s13, s15
	s_mulk_i32 s51, 0x4400
	s_mul_hi_u32 s13, s9, 0x4400
	s_add_i32 s13, s13, s51
	s_mulk_i32 s9, 0x4400
	s_add_u32 s9, s88, s9
	s_addc_u32 s51, s89, s13
	s_lshl_b32 s8, s8, 7
	s_and_b32 s8, s8, 0x380
	s_add_u32 s8, s9, s8
	s_addc_u32 s9, s51, 0
	global_load_ushort v41, v112, s[8:9] offset:2880
	global_load_ushort v81, v113, s[8:9] offset:3904
	global_load_ushort v82, v114, s[8:9] offset:832
	global_load_ushort v83, v115, s[8:9] offset:1856
	global_load_ushort v84, v116, s[8:9] offset:2880
	global_load_ushort v85, v117, s[8:9] offset:3904
	global_load_ushort v86, v118, s[8:9] offset:832
	global_load_ushort v87, v119, s[8:9] offset:1856
	v_lshl_add_u64 v[8:9], s[8:9], 0, v[156:157]
	v_lshl_add_u64 v[8:9], v[32:33], 1, v[8:9]
	v_mov_b32_e32 v190, v40
	v_mov_b32_e32 v191, v157
	v_lshl_add_u64 v[8:9], v[8:9], 0, v[190:191]
	s_movk_i32 s8, 0x5000
	v_add_co_u32_e32 v10, vcc, s8, v8
	s_mov_b32 s19, 0x9000
	s_nop 0
	v_addc_co_u32_e32 v11, vcc, 0, v9, vcc
	v_add_co_u32_e32 v12, vcc, s19, v8
	s_mov_b32 s18, 0xd000
	s_nop 0
	v_addc_co_u32_e32 v13, vcc, 0, v9, vcc
	v_add_co_u32_e32 v14, vcc, s18, v8
	s_mov_b32 s17, 0x11000
	s_nop 0
	v_addc_co_u32_e32 v15, vcc, 0, v9, vcc
	v_add_co_u32_e32 v16, vcc, s17, v8
	s_mov_b32 s16, 0x1e000
	s_nop 0
	v_addc_co_u32_e32 v17, vcc, 0, v9, vcc
	v_add_co_u32_e32 v18, vcc, s68, v8
	s_mov_b32 s8, 0x22000
	s_nop 0
	v_addc_co_u32_e32 v19, vcc, 0, v9, vcc
	v_add_co_u32_e32 v20, vcc, s73, v8
	s_nop 0
	v_addc_co_u32_e32 v21, vcc, 0, v9, vcc
	v_add_co_u32_e32 v22, vcc, s16, v8
	v_and_b32_e32 v49, 0xffff0000, v0
	s_nop 0
	v_addc_co_u32_e32 v23, vcc, 0, v9, vcc
	global_load_ushort v65, v[8:9], off offset:3904
	global_load_ushort v66, v[10:11], off offset:832
	global_load_ushort v67, v[12:13], off offset:1856
	global_load_ushort v68, v[14:15], off offset:2880
	global_load_ushort v69, v[16:17], off offset:3904
	global_load_ushort v70, v[18:19], off offset:832
	global_load_ushort v71, v[20:21], off offset:1856
	global_load_ushort v72, v[22:23], off offset:2880
	v_add_co_u32_e32 v10, vcc, s8, v8
	s_mov_b32 s8, 0x27000
	s_nop 0
	v_addc_co_u32_e32 v11, vcc, 0, v9, vcc
; DEV float bf2f(u16 h) { return __uint_as_float(((unsigned)h) << 16); }
; DEV float flog(float x) { return __builtin_amdgcn_logf(x) * 0.6931471805599453f; }
; DEV void hg_prep(int dir, int qu, int lane, char* smem, const u16 (&kr)[16], float (&g)[16], float (&kk)[16]) {
; #pragma unroll
;   for (int i = 0; i < 16; ++i) {
;     kk[i] = bf2f(kr[i]);
;     g[i] = fmaxf(flog(1.f - kk[i]), -20.f);
;   }
;   float total;
;   if (dir == 0) {
; #pragma unroll
;     for (int i = 1; i < 16; ++i) g[i] += g[i - 1];
;     total = g[15];
;   } else {
; #pragma unroll
;     for (int i = 14; i >= 0; --i) g[i] += g[i + 1];
	v_add_co_u32_e32 v12, vcc, s8, v8
	s_mov_b32 s8, 0x2b000
	s_nop 0
	v_addc_co_u32_e32 v13, vcc, 0, v9, vcc
	v_add_co_u32_e32 v14, vcc, s8, v8
	s_mov_b32 s8, 0x2f000
	s_nop 0
	v_addc_co_u32_e32 v15, vcc, 0, v9, vcc
	v_add_co_u32_e32 v16, vcc, s8, v8
	s_mov_b32 s8, 0x33000
	s_nop 0
	v_addc_co_u32_e32 v17, vcc, 0, v9, vcc
	v_add_co_u32_e32 v18, vcc, s8, v8
	s_mov_b32 s8, 0x38000
	s_nop 0
	v_addc_co_u32_e32 v19, vcc, 0, v9, vcc
	v_add_co_u32_e32 v20, vcc, s8, v8
	s_mov_b32 s8, 0x3c000
	s_nop 0
	v_addc_co_u32_e32 v21, vcc, 0, v9, vcc
	v_add_co_u32_e32 v22, vcc, s8, v8
	s_mov_b32 s8, 0x40000
	s_nop 0
	v_addc_co_u32_e32 v23, vcc, 0, v9, vcc
	v_add_co_u32_e32 v8, vcc, s8, v8
	v_addc_co_u32_e32 v9, vcc, 0, v9, vcc
	global_load_ushort v73, v[10:11], off offset:3904
	global_load_ushort v74, v[12:13], off offset:832
	global_load_ushort v75, v[14:15], off offset:1856
	global_load_ushort v76, v[16:17], off offset:2880
	global_load_ushort v77, v[18:19], off offset:3904
	global_load_ushort v78, v[20:21], off offset:832
	global_load_ushort v79, v[22:23], off offset:1856
	global_load_ushort v80, v[8:9], off offset:2880
	v_sub_f32_e32 v8, 1.0, v49
	v_log_f32_e32 v8, v8
	v_sub_f32_e32 v9, 1.0, v57
	v_log_f32_e32 v9, v9
	v_sub_f32_e32 v6, 1.0, v46
	v_mul_f32_e32 v8, 0x3f317218, v8
	v_max_f32_e32 v88, 0xc1a00000, v8
	v_log_f32_e32 v6, v6
	v_sub_f32_e32 v8, 1.0, v47
	v_log_f32_e32 v8, v8
	v_mul_f32_e32 v7, 0x3f317218, v7
	v_lshlrev_b32_e32 v54, 16, v5
	v_max_f32_e32 v89, 0xc1a00000, v7
	v_mul_f32_e32 v7, 0x3f317218, v9
	v_and_b32_e32 v55, 0xffff0000, v5
	v_sub_f32_e32 v5, 1.0, v54
	v_max_f32_e32 v90, 0xc1a00000, v7
	v_mul_f32_e32 v6, 0x3f317218, v6
	v_log_f32_e32 v7, v5
	v_sub_f32_e32 v5, 1.0, v55
	v_max_f32_e32 v91, 0xc1a00000, v6
	v_mul_f32_e32 v6, 0x3f317218, v8
	v_log_f32_e32 v8, v5
	v_lshlrev_b32_e32 v44, 16, v4
	v_and_b32_e32 v45, 0xffff0000, v4
	v_sub_f32_e32 v4, 1.0, v44
	v_max_f32_e32 v5, 0xc1a00000, v6
	v_mul_f32_e32 v6, 0x3f317218, v7
	v_mul_f32_e32 v7, 0x3f317218, v8
	v_log_f32_e32 v4, v4
	v_sub_f32_e32 v8, 1.0, v45
	v_log_f32_e32 v9, v8
	v_lshlrev_b32_e32 v52, 16, v3
	v_mul_f32_e32 v4, 0x3f317218, v4
	v_and_b32_e32 v53, 0xffff0000, v3
	v_sub_f32_e32 v3, 1.0, v52
	v_max_f32_e32 v8, 0xc1a00000, v4
	v_mul_f32_e32 v4, 0x3f317218, v9
	v_log_f32_e32 v3, v3
	v_sub_f32_e32 v9, 1.0, v53
	v_log_f32_e32 v11, v9
	v_lshlrev_b32_e32 v42, 16, v2
	v_mul_f32_e32 v3, 0x3f317218, v3
	v_lshlrev_b32_e32 v50, 16, v1
	v_lshlrev_b32_e32 v48, 16, v0
	v_max_f32_e32 v10, 0xc1a00000, v3
	v_mul_f32_e32 v3, 0x3f317218, v11
	v_and_b32_e32 v43, 0xffff0000, v2
	v_sub_f32_e32 v2, 1.0, v42
	v_and_b32_e32 v51, 0xffff0000, v1
	v_sub_f32_e32 v1, 1.0, v50
	v_sub_f32_e32 v0, 1.0, v48
	v_max_f32_e32 v9, 0xc1a00000, v4
	v_log_f32_e32 v2, v2
	v_sub_f32_e32 v4, 1.0, v43
	v_max_f32_e32 v11, 0xc1a00000, v3
	v_log_f32_e32 v1, v1
	v_sub_f32_e32 v3, 1.0, v51
	v_log_f32_e32 v0, v0
	v_log_f32_e32 v4, v4
	v_log_f32_e32 v3, v3
	v_mul_f32_e32 v2, 0x3f317218, v2
	v_mul_f32_e32 v1, 0x3f317218, v1
	v_mul_f32_e32 v0, 0x3f317218, v0
	v_max_f32_e32 v12, 0xc1a00000, v2
	v_mul_f32_e32 v2, 0x3f317218, v4
	v_max_f32_e32 v14, 0xc1a00000, v1
	v_mul_f32_e32 v1, 0x3f317218, v3
	v_max_f32_e32 v0, 0xc1a00000, v0
	v_max_f32_e32 v6, 0xc1a00000, v6
	v_max_f32_e32 v7, 0xc1a00000, v7
	v_max_f32_e32 v13, 0xc1a00000, v2
	v_max_f32_e32 v15, 0xc1a00000, v1
	s_and_saveexec_b64 s[8:9], s[40:41]
	s_xor_b64 s[8:9], exec, s[8:9]
	s_cbranch_execz .LBB0_736
	v_add_f32_e32 v14, v14, v15
	v_add_f32_e32 v13, v13, v14
	v_add_f32_e32 v12, v12, v13
	v_add_f32_e32 v11, v11, v12
	v_add_f32_e32 v10, v10, v11
	v_add_f32_e32 v9, v9, v10
	v_add_f32_e32 v8, v8, v9
	v_add_f32_e32 v7, v7, v8
	v_add_f32_e32 v6, v6, v7
	v_add_f32_e32 v5, v5, v6
	v_add_f32_e32 v4, v91, v5
	v_add_f32_e32 v3, v90, v4
	v_add_f32_e32 v2, v89, v3
	v_add_f32_e32 v1, v88, v2
	v_add_f32_e32 v0, v0, v1
	v_mov_b64_e32 v[30:31], v[14:15]
	v_mov_b64_e32 v[28:29], v[12:13]
	v_mov_b64_e32 v[26:27], v[10:11]
	v_mov_b64_e32 v[24:25], v[8:9]
	v_mov_b64_e32 v[22:23], v[6:7]
	v_mov_b64_e32 v[20:21], v[4:5]
	v_mov_b64_e32 v[18:19], v[2:3]
	v_mov_b64_e32 v[16:17], v[0:1]
